# v7 + L0 half-step wave stagger + s_setprio 1 during the PV-chain phase
# baseline (speedup 1.0000x reference)
; __global__ void __launch_bounds__(NWAVES * 64, 2) mega_fwd(Args args) {
;     ...
;         if (layer == 0) {
;             for (int idx = vcu; idx < 1024 + 4096; idx += G) {
;                 size_t tok0; int head, kvh, qb, NT;
;                 if (idx < 1024) { const int xcd = (idx >> 5) & 7, j = idx & 31, i = idx >> 8; kvh = xcd & 3; const int w = (((xcd >> 2) * 4 + i) << 5) + j; head = kvh * 4 + (w >> 6); qb = w & 63; tok0 = MP; NT = LS / 64; }
;                 else { const int id2 = idx - 1024; const int xcd = (id2 >> 5) & 7, j = id2 & 31, i = id2 >> 8; const int gq = xcd * 16 + i; kvh = gq & 3; head = kvh * 4 + (j >> 3); qb = j & 7; tok0 = (size_t)(gq >> 2) * LP; NT = LP / 64; }
;                 attn_body::attn_unit2<1, false, 0>((const attn_body::bf16*)(Qb + tok0 * 1024 + head * 64), 1024, (const attn_body::bf16*)(Kb + tok0 * 256 + kvh * 64), 256,
;                     (const attn_body::bf16*)(Vb + tok0 * 256 + kvh * 64), 256, (attn_body::bf16*)(Ob + tok0 * 1024 + head * 64), 1024, qb * 256, NT, nullptr, (char*)lds + RING_OFF, 0.f, nullptr, 0.f); }
.LBB0_607:
	s_or_b64 exec, exec, s[4:5]
	s_cmpk_gt_i32 s72, 0x13ff
	s_waitcnt lgkmcnt(0)
	s_barrier
	s_cbranch_scc1 .LBB0_647
	v_readfirstlane_b32 s99, v182
	s_nop 3
	s_lshr_b32 s99, s99, 8
	s_add_u32 s33, s30, 0x18000000
	s_addc_u32 s46, s31, 0
	s_add_u32 s47, s30, 0x22000000
	s_addc_u32 s48, s31, 0
	s_add_u32 s49, s30, 0x2c000000
	s_addc_u32 s50, s31, 0
	s_mov_b32 s5, 0
	v_mov_b32_e32 v159, 0
	s_mov_b32 s51, s72
	s_branch .LBB0_610

;   #define RSCALE(t) do{ if(HAS_BIAS&&((t)==tn0||(t)==tn1)){ const float f_=__builtin_amdgcn_exp2f(CREG((t)-1)-CREG(t)); l_reg*=f_; \
;     _Pragma("unroll") for(int d_=0;d_<2*VH;++d_) _Pragma("unroll") for(int r=0;r<16;++r)o[d_][r]*=f_; } }while(0)
;   #define ROT() do{sv_prev=sv_cur;sv_cur=sv_next;sv_next=(sv_next==2*VSL)?0:sv_next+VSL;}while(0)
;   #define WAITFULL() do{ if(VH==1){WAIT_BAR(2);}else{WAIT_BAR(3);} }while(0)
; template<int VH,bool HAS_BIAS,int MODE> __device__ __forceinline__ void attn_unit2(const bf16*Qb,int qp,const bf16*__restrict__ Kb,int kp,const bf16*__restrict__ Vb,int vp,bf16*Ob,int op,int q0,int NT,const float*relb,char*shm,float lam,const float*subg,float gmul){
;     ...
;   int t=1;
;   for(;t+5<NT;t+=2){
;     STEP(pB0,pB1,pA0,pA1,t,true,true,true);     WAITFULL(); RSCALE(t);   ROT();
;     STEP(pA0,pA1,pB0,pB1,t+1,true,true,true);   WAITFULL(); RSCALE(t+1); ROT();
.LBB0_615:
	s_mov_b32 s62, s60
	s_mov_b32 s60, s56
	s_mov_b32 s58, s66
	s_mov_b64 s[22:23], s[44:45]
	s_mov_b32 s59, s65
	v_add_u32_e32 v148, s64, v167
	ds_read_b64_tr_b16 v[140:141], v148 offset:32768
	ds_read_b64_tr_b16 v[142:143], v148 offset:33280
	s_add_i32 s14, s63, 0xffffe000
	s_and_b32 s44, s14, 0x6000
	v_add_u32_e32 v96, s44, v164
	s_waitcnt lgkmcnt(2)
	v_mfma_f32_32x32x16_bf16 v[80:95], v[80:83], v[124:127], 0
	v_add_f32_e32 v64, v48, v49
	v_add_f32_e32 v64, v50, v64
	v_add_f32_e32 v64, v51, v64
	v_add_f32_e32 v64, v52, v64
	v_add_f32_e32 v64, v53, v64
	v_cvt_pk_bf16_f32 v108, v48, v49
	v_cvt_pk_bf16_f32 v109, v50, v51
	ds_read_b64_tr_b16 v[48:49], v148 offset:36864
	ds_read_b64_tr_b16 v[50:51], v148 offset:37376
	v_add_f32_e32 v64, v54, v64
	v_add_f32_e32 v64, v55, v64
	v_add_f32_e32 v64, v56, v64
	v_add_f32_e32 v97, v57, v64
	v_cvt_pk_bf16_f32 v110, v52, v53
	v_cvt_pk_bf16_f32 v111, v54, v55
	v_mfma_f32_32x32x16_bf16 v[64:79], v[136:139], v[124:127], 0
	ds_read_b128 v[52:55], v96 offset:4096
	ds_read_b128 v[136:139], v96 offset:4608
	ds_read_b64_tr_b16 v[144:145], v148 offset:33792
	ds_read_b64_tr_b16 v[146:147], v148 offset:34304
	v_mfma_f32_32x32x16_bf16 v[80:95], v[132:135], v[120:123], v[80:95]
	v_add_f32_e32 v97, v58, v97
	v_add_f32_e32 v97, v59, v97
	v_add_f32_e32 v97, v60, v97
	v_add_f32_e32 v97, v61, v97
	v_cvt_pk_bf16_f32 v104, v56, v57
	v_cvt_pk_bf16_f32 v105, v58, v59
	ds_read_b64_tr_b16 v[56:57], v148 offset:37888
	ds_read_b64_tr_b16 v[58:59], v148 offset:38400
	v_add_f32_e32 v97, v62, v97
	v_add_f32_e32 v97, v63, v97
	v_add_f32_e32 v97, v32, v97
	v_add_f32_e32 v97, v33, v97
	v_cvt_pk_bf16_f32 v106, v60, v61
	v_cvt_pk_bf16_f32 v107, v62, v63
	v_mfma_f32_32x32x16_bf16 v[64:79], v[128:131], v[120:123], v[64:79]
	ds_read_b128 v[60:63], v96 offset:6144
	ds_read_b128 v[128:131], v96 offset:6656
	ds_read_b64_tr_b16 v[132:133], v148 offset:34816
	ds_read_b64_tr_b16 v[134:135], v148 offset:35328
	s_waitcnt lgkmcnt(9)
	v_mfma_f32_32x32x16_bf16 v[80:95], v[52:55], v[116:119], v[80:95]
	v_add_f32_e32 v96, v34, v97
	v_add_f32_e32 v96, v35, v96
	v_add_f32_e32 v96, v36, v96
	v_add_f32_e32 v96, v37, v96
	v_cvt_pk_bf16_f32 v100, v32, v33
	v_cvt_pk_bf16_f32 v101, v34, v35
	ds_read_b64_tr_b16 v[32:33], v148 offset:38912
	ds_read_b64_tr_b16 v[34:35], v148 offset:39424
	v_add_f32_e32 v52, v38, v96
	v_add_f32_e32 v52, v39, v52
	v_add_f32_e32 v52, v40, v52
	v_add_f32_e32 v52, v41, v52
	v_cvt_pk_bf16_f32 v102, v36, v37
	v_cvt_pk_bf16_f32 v103, v38, v39
	s_waitcnt lgkmcnt(10)
	v_mfma_f32_32x32x16_bf16 v[64:79], v[136:139], v[116:119], v[64:79]
	ds_read_b64_tr_b16 v[36:37], v148 offset:35840
	ds_read_b64_tr_b16 v[38:39], v148 offset:36352
	s_waitcnt lgkmcnt(7)
	v_mfma_f32_32x32x16_bf16 v[80:95], v[60:63], v[112:115], v[80:95]
	v_add_f32_e32 v52, v42, v52
	v_add_f32_e32 v52, v43, v52
	v_add_f32_e32 v52, v44, v52
	v_add_f32_e32 v52, v45, v52
	v_cvt_pk_bf16_f32 v96, v40, v41
	v_cvt_pk_bf16_f32 v97, v42, v43
	ds_read_b64_tr_b16 v[40:41], v148 offset:39936
	ds_read_b64_tr_b16 v[42:43], v148 offset:40448
	v_add_f32_e32 v52, v46, v52
	v_add_f32_e32 v52, v47, v52
	v_add_f32_e32 v52, 0, v52
	v_cvt_pk_bf16_f32 v98, v44, v45
	v_cvt_pk_bf16_f32 v99, v46, v47
	s_waitcnt lgkmcnt(8)
	v_mfma_f32_32x32x16_bf16 v[64:79], v[128:131], v[112:115], v[64:79]
	s_add_u32 s34, s42, 0xffff8000
	s_addc_u32 s35, s43, -1
	s_add_i32 s64, s63, 0x4000
	s_and_b32 s14, s64, 0x6000
	s_add_i32 s14, s14, s54
	s_mov_b32 m0, s14
	s_nop 0
	global_load_lds_dwordx4 v169, s[34:35]
	s_add_u32 s34, s40, 0xffff8000
	s_addc_u32 s35, s41, -1
	s_add_i32 s14, s62, s55
	s_mov_b32 m0, s14
	s_nop 0
	global_load_lds_dwordx4 v170, s[34:35]
	v_add_f32_e32 v148, v168, v52
	s_cmp_eq_u32 s99, 0
	s_cbranch_scc1 .Lstgc_m0
	s_waitcnt vmcnt(2) lgkmcnt(0)
	s_barrier
.Lstgc_m0:
	s_setprio 1
	v_mfma_f32_32x32x16_bf16 v[0:15], v[108:111], v[140:143], v[0:15]
	v_exp_f32_e32 v80, v80
	v_exp_f32_e32 v81, v81
	v_exp_f32_e32 v82, v82
	v_exp_f32_e32 v83, v83
	s_waitcnt lgkmcnt(12)
	v_mfma_f32_32x32x16_bf16 v[0:15], v[104:107], v[144:147], v[0:15]
	v_exp_f32_e32 v84, v84
	v_exp_f32_e32 v85, v85
	v_exp_f32_e32 v86, v86
	v_exp_f32_e32 v87, v87
	s_waitcnt lgkmcnt(6)
	v_mfma_f32_32x32x16_bf16 v[0:15], v[100:103], v[132:135], v[0:15]
	v_exp_f32_e32 v88, v88
	v_exp_f32_e32 v89, v89
	v_exp_f32_e32 v90, v90
	v_exp_f32_e32 v91, v91
	s_waitcnt lgkmcnt(2)
	v_mfma_f32_32x32x16_bf16 v[0:15], v[96:99], v[36:39], v[0:15]
	v_exp_f32_e32 v92, v92
	v_exp_f32_e32 v93, v93
	v_exp_f32_e32 v94, v94
	v_exp_f32_e32 v95, v95
	v_mfma_f32_32x32x16_bf16 v[16:31], v[108:111], v[48:51], v[16:31]
	v_exp_f32_e32 v64, v64
	v_exp_f32_e32 v65, v65
	v_exp_f32_e32 v66, v66
	v_exp_f32_e32 v67, v67
	s_and_b32 s14, s63, 0x6000
	v_add_u32_e32 v149, s14, v164
	ds_read_b128 v[44:47], v149
	ds_read_b128 v[128:131], v149 offset:512
	ds_read_b128 v[136:139], v149 offset:2048
	ds_read_b128 v[140:143], v149 offset:2560
	v_mfma_f32_32x32x16_bf16 v[16:31], v[104:107], v[56:59], v[16:31]
	v_exp_f32_e32 v68, v68
	v_exp_f32_e32 v69, v69
	v_exp_f32_e32 v70, v70
	v_exp_f32_e32 v71, v71
	v_mfma_f32_32x32x16_bf16 v[16:31], v[100:103], v[32:35], v[16:31]
	v_exp_f32_e32 v72, v72
	v_exp_f32_e32 v73, v73
	v_exp_f32_e32 v74, v74
	v_exp_f32_e32 v75, v75
	s_waitcnt lgkmcnt(4)
	v_mfma_f32_32x32x16_bf16 v[16:31], v[96:99], v[40:43], v[16:31]
	v_exp_f32_e32 v76, v76
	v_exp_f32_e32 v77, v77
	v_exp_f32_e32 v78, v78
	v_exp_f32_e32 v79, v79
	s_setprio 0
	s_cmp_lg_u32 s99, 0
	s_cbranch_scc1 .Lstgc_e0
	s_waitcnt vmcnt(2) lgkmcnt(0)
	s_barrier
;   #define RSCALE(t) do{ if(HAS_BIAS&&((t)==tn0||(t)==tn1)){ const float f_=__builtin_amdgcn_exp2f(CREG((t)-1)-CREG(t)); l_reg*=f_; \
;     _Pragma("unroll") for(int d_=0;d_<2*VH;++d_) _Pragma("unroll") for(int r=0;r<16;++r)o[d_][r]*=f_; } }while(0)
;   #define ROT() do{sv_prev=sv_cur;sv_cur=sv_next;sv_next=(sv_next==2*VSL)?0:sv_next+VSL;}while(0)
;   #define WAITFULL() do{ if(VH==1){WAIT_BAR(2);}else{WAIT_BAR(3);} }while(0)
; template<int VH,bool HAS_BIAS,int MODE> __device__ __forceinline__ void attn_unit2(const bf16*Qb,int qp,const bf16*__restrict__ Kb,int kp,const bf16*__restrict__ Vb,int vp,bf16*Ob,int op,int q0,int NT,const float*relb,char*shm,float lam,const float*subg,float gmul){
;     ...
;   int t=1;
;   for(;t+5<NT;t+=2){
;     STEP(pB0,pB1,pA0,pA1,t,true,true,true);     WAITFULL(); RSCALE(t);   ROT();
;     STEP(pA0,pA1,pB0,pB1,t+1,true,true,true);   WAITFULL(); RSCALE(t+1); ROT();
.Lstgc_e0:
	s_add_i32 s14, s62, 0x2000
	s_cmpk_lg_i32 s62, 0x4000
	s_cselect_b32 s56, s14, 0
	v_add_u32_e32 v150, s60, v167
	ds_read_b64_tr_b16 v[132:133], v150 offset:32768
	ds_read_b64_tr_b16 v[134:135], v150 offset:33280
	s_waitcnt lgkmcnt(5)
	v_mfma_f32_32x32x16_bf16 v[48:63], v[44:47], v[124:127], 0
	v_add_f32_e32 v32, v80, v81
	v_add_f32_e32 v32, v82, v32
	v_add_f32_e32 v32, v83, v32
	v_add_f32_e32 v32, v84, v32
	v_add_f32_e32 v32, v85, v32
	v_cvt_pk_bf16_f32 v108, v80, v81
	v_cvt_pk_bf16_f32 v109, v82, v83
	ds_read_b64_tr_b16 v[80:81], v150 offset:36864
	ds_read_b64_tr_b16 v[82:83], v150 offset:37376
	v_add_f32_e32 v32, v86, v32
	v_add_f32_e32 v32, v87, v32
	v_add_f32_e32 v32, v88, v32
	v_add_f32_e32 v96, v89, v32
	s_waitcnt lgkmcnt(6)
	v_mfma_f32_32x32x16_bf16 v[32:47], v[128:131], v[124:127], 0
	v_cvt_pk_bf16_f32 v110, v84, v85
	v_cvt_pk_bf16_f32 v111, v86, v87
	ds_read_b128 v[84:87], v149 offset:4096
	ds_read_b128 v[128:131], v149 offset:4608
	ds_read_b64_tr_b16 v[144:145], v150 offset:33792
	ds_read_b64_tr_b16 v[146:147], v150 offset:34304
	s_waitcnt lgkmcnt(9)
	v_mfma_f32_32x32x16_bf16 v[48:63], v[136:139], v[120:123], v[48:63]
	v_add_f32_e32 v96, v90, v96
	v_add_f32_e32 v96, v91, v96
	v_add_f32_e32 v96, v92, v96
	v_add_f32_e32 v96, v93, v96
	v_cvt_pk_bf16_f32 v104, v88, v89
	v_cvt_pk_bf16_f32 v105, v90, v91
	ds_read_b64_tr_b16 v[88:89], v150 offset:37888
	ds_read_b64_tr_b16 v[90:91], v150 offset:38400
	s_waitcnt lgkmcnt(10)
	v_mfma_f32_32x32x16_bf16 v[32:47], v[140:143], v[120:123], v[32:47]
	v_add_f32_e32 v96, v94, v96
	v_add_f32_e32 v96, v95, v96
	v_add_f32_e32 v96, v64, v96
	v_add_f32_e32 v96, v65, v96
	v_cvt_pk_bf16_f32 v106, v92, v93
	v_cvt_pk_bf16_f32 v107, v94, v95
	ds_read_b128 v[92:95], v149 offset:6144
	ds_read_b128 v[136:139], v149 offset:6656
	ds_read_b64_tr_b16 v[140:141], v150 offset:34816
	ds_read_b64_tr_b16 v[142:143], v150 offset:35328
	s_waitcnt lgkmcnt(9)
	v_mfma_f32_32x32x16_bf16 v[48:63], v[84:87], v[116:119], v[48:63]
	v_add_f32_e32 v96, v66, v96
	v_add_f32_e32 v96, v67, v96
	v_add_f32_e32 v96, v68, v96
	v_add_f32_e32 v96, v69, v96
	v_cvt_pk_bf16_f32 v100, v64, v65
	v_cvt_pk_bf16_f32 v101, v66, v67
	ds_read_b64_tr_b16 v[64:65], v150 offset:38912
	ds_read_b64_tr_b16 v[66:67], v150 offset:39424
	s_waitcnt lgkmcnt(10)
	v_mfma_f32_32x32x16_bf16 v[32:47], v[128:131], v[116:119], v[32:47]
	v_add_f32_e32 v84, v70, v96
	v_add_f32_e32 v84, v71, v84
	v_add_f32_e32 v84, v72, v84
	v_add_f32_e32 v84, v73, v84
	v_cvt_pk_bf16_f32 v102, v68, v69
	v_cvt_pk_bf16_f32 v103, v70, v71
	ds_read_b64_tr_b16 v[68:69], v150 offset:35840
	ds_read_b64_tr_b16 v[70:71], v150 offset:36352
	s_waitcnt lgkmcnt(7)
	v_mfma_f32_32x32x16_bf16 v[48:63], v[92:95], v[112:115], v[48:63]
	v_add_f32_e32 v84, v74, v84
	v_add_f32_e32 v84, v75, v84
	v_add_f32_e32 v84, v76, v84
	v_add_f32_e32 v84, v77, v84
	v_cvt_pk_bf16_f32 v96, v72, v73
	v_cvt_pk_bf16_f32 v97, v74, v75
	ds_read_b64_tr_b16 v[72:73], v150 offset:39936
	ds_read_b64_tr_b16 v[74:75], v150 offset:40448
	s_waitcnt lgkmcnt(8)
	v_mfma_f32_32x32x16_bf16 v[32:47], v[136:139], v[112:115], v[32:47]
	v_add_f32_e32 v84, v78, v84
	v_add_f32_e32 v84, v79, v84
	v_add_f32_e32 v84, 0, v84
	v_cvt_pk_bf16_f32 v98, v76, v77
	v_cvt_pk_bf16_f32 v99, v78, v79
	s_add_i32 s14, s44, s54
	s_mov_b32 m0, s14
	s_nop 0
	global_load_lds_dwordx4 v169, s[42:43]
	s_add_i32 s14, s56, s55
	s_mov_b32 m0, s14
	s_nop 0
	global_load_lds_dwordx4 v170, s[40:41]
	v_add_f32_e32 v168, v148, v84
	s_add_i32 s57, s57, 2
	s_cmp_eq_u32 s99, 0
	s_cbranch_scc1 .Lstgc_m1
	s_waitcnt vmcnt(2) lgkmcnt(0)
	s_barrier
.Lstgc_m1:
	s_setprio 1
	v_mfma_f32_32x32x16_bf16 v[0:15], v[108:111], v[132:135], v[0:15]
	v_exp_f32_e32 v48, v48
	v_exp_f32_e32 v49, v49
	v_exp_f32_e32 v50, v50
	v_exp_f32_e32 v51, v51
	s_waitcnt lgkmcnt(12)
	v_mfma_f32_32x32x16_bf16 v[0:15], v[104:107], v[144:147], v[0:15]
	v_exp_f32_e32 v52, v52
	v_exp_f32_e32 v53, v53
	v_exp_f32_e32 v54, v54
	v_exp_f32_e32 v55, v55
	s_waitcnt lgkmcnt(6)
	v_mfma_f32_32x32x16_bf16 v[0:15], v[100:103], v[140:143], v[0:15]
	v_exp_f32_e32 v56, v56
	v_exp_f32_e32 v57, v57
	v_exp_f32_e32 v58, v58
	v_exp_f32_e32 v59, v59
	s_waitcnt lgkmcnt(2)
	v_mfma_f32_32x32x16_bf16 v[0:15], v[96:99], v[68:71], v[0:15]
	v_exp_f32_e32 v60, v60
	v_exp_f32_e32 v61, v61
	v_exp_f32_e32 v62, v62
	v_exp_f32_e32 v63, v63
	v_mfma_f32_32x32x16_bf16 v[16:31], v[108:111], v[80:83], v[16:31]
	v_exp_f32_e32 v32, v32
	v_exp_f32_e32 v33, v33
	v_exp_f32_e32 v34, v34
	v_exp_f32_e32 v35, v35
	s_add_i32 s14, s63, 0x2000
	s_and_b32 s14, s14, 0x6000
	v_add_u32_e32 v76, s14, v164
	ds_read_b128 v[80:83], v76
	ds_read_b128 v[136:139], v76 offset:512
	ds_read_b128 v[132:135], v76 offset:2048
	ds_read_b128 v[128:131], v76 offset:2560
	v_mfma_f32_32x32x16_bf16 v[16:31], v[104:107], v[88:91], v[16:31]
	v_exp_f32_e32 v36, v36
	v_exp_f32_e32 v37, v37
	v_exp_f32_e32 v38, v38
	v_exp_f32_e32 v39, v39
	v_mfma_f32_32x32x16_bf16 v[16:31], v[100:103], v[64:67], v[16:31]
	v_exp_f32_e32 v40, v40
	v_exp_f32_e32 v41, v41
	v_exp_f32_e32 v42, v42
	v_exp_f32_e32 v43, v43
	s_waitcnt lgkmcnt(4)
	v_mfma_f32_32x32x16_bf16 v[16:31], v[96:99], v[72:75], v[16:31]
	v_exp_f32_e32 v44, v44
	v_exp_f32_e32 v45, v45
	v_exp_f32_e32 v46, v46
	v_exp_f32_e32 v47, v47
	s_add_i32 s14, s56, 0x2000
	s_cmpk_lg_i32 s56, 0x4000
	s_cselect_b32 s60, s14, 0
	s_add_u32 s40, s40, 0x10000
	s_addc_u32 s41, s41, 0
	s_add_u32 s42, s42, 0x10000
	s_addc_u32 s43, s43, 0
	s_addk_i32 s66, 0x4000
	s_setprio 0
	s_cmp_lg_u32 s99, 0
	s_cbranch_scc1 .Lstgc_e1
	s_waitcnt vmcnt(2) lgkmcnt(0)
	s_barrier
.Lstgc_e1:
	s_add_u32 s44, s22, 0x10000
	s_addc_u32 s45, s23, 0
	s_add_i32 s65, s65, 2
	s_cmp_ge_u32 s57, s61
	s_mov_b32 s63, s64
	s_mov_b32 s64, s62
	s_cbranch_scc0 .LBB0_615
	s_add_i32 s14, s57, 1
	s_cmp_ge_u32 s14, s53
	s_cbranch_scc1 .LBB0_644
	s_add_i32 s61, s53, -2
